# P2.5 sigmoid epilogue rewritten: bias and scale fused into packed fma, packed +1, results converted in place
# speedup vs baseline: 1.0044x; 1.0044x over previous
.LBB0_540:
	v_lshl_or_b32 v90, s69, 8, v161
	v_ashrrev_i32_e32 v91, 31, v90
	v_lshl_add_u64 v[90:91], v[90:91], 2, s[28:29]
	global_load_dwordx4 v[102:105], v[90:91], off
	global_load_dwordx4 v[98:101], v[90:91], off offset:16
	global_load_dwordx4 v[94:97], v[90:91], off offset:512
	s_nop 0
	global_load_dwordx4 v[90:93], v[90:91], off offset:528
	s_mul_i32 s43, s70, 12
	s_add_i32 s60, s43, s69
	s_ashr_i32 s61, s60, 31
	s_lshl_b64 s[60:61], s[60:61], 17
	s_add_u32 s60, s60, 0x1000
	s_addc_u32 s61, s61, 0
	v_lshl_add_u64 v[158:159], v[152:153], 0, s[60:61]
	s_mov_b32 s60, 0xbfb8aa3b
	s_mov_b32 s61, 0xbfb8aa3b
	s_waitcnt vmcnt(0)
	v_pk_mul_f32 v[102:103], v[102:103], s[60:61]
	v_pk_mul_f32 v[104:105], v[104:105], s[60:61]
	v_pk_mul_f32 v[98:99], v[98:99], s[60:61]
	v_pk_mul_f32 v[100:101], v[100:101], s[60:61]
	v_pk_mul_f32 v[94:95], v[94:95], s[60:61]
	v_pk_mul_f32 v[96:97], v[96:97], s[60:61]
	v_pk_mul_f32 v[90:91], v[90:91], s[60:61]
	v_pk_mul_f32 v[92:93], v[92:93], s[60:61]
	v_pk_fma_f32 v[142:143], v[142:143], s[60:61], v[102:103]
	v_pk_fma_f32 v[144:145], v[144:145], s[60:61], v[104:105]
	v_pk_fma_f32 v[138:139], v[138:139], s[60:61], v[98:99]
	v_pk_fma_f32 v[140:141], v[140:141], s[60:61], v[100:101]
	v_exp_f32_e32 v142, v142
	v_exp_f32_e32 v143, v143
	v_exp_f32_e32 v144, v144
	v_exp_f32_e32 v145, v145
	v_exp_f32_e32 v138, v138
	v_exp_f32_e32 v139, v139
	v_exp_f32_e32 v140, v140
	v_exp_f32_e32 v141, v141
	v_pk_add_f32 v[142:143], v[142:143], 1.0 op_sel_hi:[1,0]
	v_pk_add_f32 v[144:145], v[144:145], 1.0 op_sel_hi:[1,0]
	v_pk_add_f32 v[138:139], v[138:139], 1.0 op_sel_hi:[1,0]
	v_pk_add_f32 v[140:141], v[140:141], 1.0 op_sel_hi:[1,0]
	v_rcp_f32_e32 v142, v142
	v_rcp_f32_e32 v143, v143
	v_rcp_f32_e32 v144, v144
	v_rcp_f32_e32 v145, v145
	v_rcp_f32_e32 v138, v138
	v_rcp_f32_e32 v139, v139
	v_rcp_f32_e32 v140, v140
	v_rcp_f32_e32 v141, v141
	v_max_f32_e32 v142, 0x219392ef, v142
	v_max_f32_e32 v143, 0x219392ef, v143
	v_max_f32_e32 v144, 0x219392ef, v144
	v_max_f32_e32 v145, 0x219392ef, v145
	v_max_f32_e32 v138, 0x219392ef, v138
	v_max_f32_e32 v139, 0x219392ef, v139
	v_max_f32_e32 v140, 0x219392ef, v140
	v_max_f32_e32 v141, 0x219392ef, v141
	v_cvt_pk_bf16_f32 v142, v142, v143
	v_cvt_pk_bf16_f32 v143, v144, v145
	v_cvt_pk_bf16_f32 v144, v138, v139
	v_cvt_pk_bf16_f32 v145, v140, v141
	global_store_dwordx4 v[158:159], v[142:145], off offset:-4096 sc1
	v_pk_fma_f32 v[134:135], v[134:135], s[60:61], v[94:95]
	v_pk_fma_f32 v[136:137], v[136:137], s[60:61], v[96:97]
	v_pk_fma_f32 v[130:131], v[130:131], s[60:61], v[90:91]
	v_pk_fma_f32 v[132:133], v[132:133], s[60:61], v[92:93]
	v_exp_f32_e32 v134, v134
	v_exp_f32_e32 v135, v135
	v_exp_f32_e32 v136, v136
	v_exp_f32_e32 v137, v137
	v_exp_f32_e32 v130, v130
	v_exp_f32_e32 v131, v131
	v_exp_f32_e32 v132, v132
	v_exp_f32_e32 v133, v133
	v_pk_add_f32 v[134:135], v[134:135], 1.0 op_sel_hi:[1,0]
	v_pk_add_f32 v[136:137], v[136:137], 1.0 op_sel_hi:[1,0]
	v_pk_add_f32 v[130:131], v[130:131], 1.0 op_sel_hi:[1,0]
	v_pk_add_f32 v[132:133], v[132:133], 1.0 op_sel_hi:[1,0]
	v_rcp_f32_e32 v134, v134
	v_rcp_f32_e32 v135, v135
	v_rcp_f32_e32 v136, v136
	v_rcp_f32_e32 v137, v137
	v_rcp_f32_e32 v130, v130
	v_rcp_f32_e32 v131, v131
	v_rcp_f32_e32 v132, v132
	v_rcp_f32_e32 v133, v133
	v_max_f32_e32 v134, 0x219392ef, v134
	v_max_f32_e32 v135, 0x219392ef, v135
	v_max_f32_e32 v136, 0x219392ef, v136
	v_max_f32_e32 v137, 0x219392ef, v137
	v_max_f32_e32 v130, 0x219392ef, v130
	v_max_f32_e32 v131, 0x219392ef, v131
	v_max_f32_e32 v132, 0x219392ef, v132
	v_max_f32_e32 v133, 0x219392ef, v133
	v_cvt_pk_bf16_f32 v134, v134, v135
	v_cvt_pk_bf16_f32 v135, v136, v137
	v_cvt_pk_bf16_f32 v136, v130, v131
	v_cvt_pk_bf16_f32 v137, v132, v133
	global_store_dwordx4 v[158:159], v[134:137], off offset:-3072 sc1
	v_pk_fma_f32 v[126:127], v[126:127], s[60:61], v[102:103]
	v_pk_fma_f32 v[128:129], v[128:129], s[60:61], v[104:105]
	v_pk_fma_f32 v[122:123], v[122:123], s[60:61], v[98:99]
	v_pk_fma_f32 v[124:125], v[124:125], s[60:61], v[100:101]
	v_exp_f32_e32 v126, v126
	v_exp_f32_e32 v127, v127
	v_exp_f32_e32 v128, v128
	v_exp_f32_e32 v129, v129
	v_exp_f32_e32 v122, v122
	v_exp_f32_e32 v123, v123
	v_exp_f32_e32 v124, v124
	v_exp_f32_e32 v125, v125
	v_pk_add_f32 v[126:127], v[126:127], 1.0 op_sel_hi:[1,0]
	v_pk_add_f32 v[128:129], v[128:129], 1.0 op_sel_hi:[1,0]
	v_pk_add_f32 v[122:123], v[122:123], 1.0 op_sel_hi:[1,0]
	v_pk_add_f32 v[124:125], v[124:125], 1.0 op_sel_hi:[1,0]
	v_rcp_f32_e32 v126, v126
	v_rcp_f32_e32 v127, v127
	v_rcp_f32_e32 v128, v128
	v_rcp_f32_e32 v129, v129
	v_rcp_f32_e32 v122, v122
	v_rcp_f32_e32 v123, v123
	v_rcp_f32_e32 v124, v124
	v_rcp_f32_e32 v125, v125
	v_max_f32_e32 v126, 0x219392ef, v126
	v_max_f32_e32 v127, 0x219392ef, v127
	v_max_f32_e32 v128, 0x219392ef, v128
	v_max_f32_e32 v129, 0x219392ef, v129
	v_max_f32_e32 v122, 0x219392ef, v122
	v_max_f32_e32 v123, 0x219392ef, v123
	v_max_f32_e32 v124, 0x219392ef, v124
	v_max_f32_e32 v125, 0x219392ef, v125
	v_cvt_pk_bf16_f32 v126, v126, v127
	v_cvt_pk_bf16_f32 v127, v128, v129
	v_cvt_pk_bf16_f32 v128, v122, v123
	v_cvt_pk_bf16_f32 v129, v124, v125
	global_store_dwordx4 v[158:159], v[126:129], off offset:-2048 sc1
	v_pk_fma_f32 v[118:119], v[118:119], s[60:61], v[94:95]
	v_pk_fma_f32 v[120:121], v[120:121], s[60:61], v[96:97]
	v_pk_fma_f32 v[114:115], v[114:115], s[60:61], v[90:91]
	v_pk_fma_f32 v[116:117], v[116:117], s[60:61], v[92:93]
	v_exp_f32_e32 v118, v118
	v_exp_f32_e32 v119, v119
	v_exp_f32_e32 v120, v120
	v_exp_f32_e32 v121, v121
	v_exp_f32_e32 v114, v114
	v_exp_f32_e32 v115, v115
	v_exp_f32_e32 v116, v116
	v_exp_f32_e32 v117, v117
	v_pk_add_f32 v[118:119], v[118:119], 1.0 op_sel_hi:[1,0]
	v_pk_add_f32 v[120:121], v[120:121], 1.0 op_sel_hi:[1,0]
	v_pk_add_f32 v[114:115], v[114:115], 1.0 op_sel_hi:[1,0]
	v_pk_add_f32 v[116:117], v[116:117], 1.0 op_sel_hi:[1,0]
	v_rcp_f32_e32 v118, v118
	v_rcp_f32_e32 v119, v119
	v_rcp_f32_e32 v120, v120
	v_rcp_f32_e32 v121, v121
	v_rcp_f32_e32 v114, v114
	v_rcp_f32_e32 v115, v115
	v_rcp_f32_e32 v116, v116
	v_rcp_f32_e32 v117, v117
	v_max_f32_e32 v118, 0x219392ef, v118
	v_max_f32_e32 v119, 0x219392ef, v119
	v_max_f32_e32 v120, 0x219392ef, v120
	v_max_f32_e32 v121, 0x219392ef, v121
	v_max_f32_e32 v114, 0x219392ef, v114
	v_max_f32_e32 v115, 0x219392ef, v115
	v_max_f32_e32 v116, 0x219392ef, v116
	v_max_f32_e32 v117, 0x219392ef, v117
	v_cvt_pk_bf16_f32 v118, v118, v119
	v_cvt_pk_bf16_f32 v119, v120, v121
	v_cvt_pk_bf16_f32 v120, v114, v115
	v_cvt_pk_bf16_f32 v121, v116, v117
	global_store_dwordx4 v[158:159], v[118:121], off offset:-1024 sc1
	v_pk_fma_f32 v[110:111], v[110:111], s[60:61], v[102:103]
	v_pk_fma_f32 v[112:113], v[112:113], s[60:61], v[104:105]
	v_pk_fma_f32 v[106:107], v[106:107], s[60:61], v[98:99]
	v_pk_fma_f32 v[108:109], v[108:109], s[60:61], v[100:101]
	v_exp_f32_e32 v110, v110
	v_exp_f32_e32 v111, v111
	v_exp_f32_e32 v112, v112
	v_exp_f32_e32 v113, v113
	v_exp_f32_e32 v106, v106
	v_exp_f32_e32 v107, v107
	v_exp_f32_e32 v108, v108
	v_exp_f32_e32 v109, v109
	v_pk_add_f32 v[110:111], v[110:111], 1.0 op_sel_hi:[1,0]
	v_pk_add_f32 v[112:113], v[112:113], 1.0 op_sel_hi:[1,0]
	v_pk_add_f32 v[106:107], v[106:107], 1.0 op_sel_hi:[1,0]
	v_pk_add_f32 v[108:109], v[108:109], 1.0 op_sel_hi:[1,0]
	v_rcp_f32_e32 v110, v110
	v_rcp_f32_e32 v111, v111
	v_rcp_f32_e32 v112, v112
	v_rcp_f32_e32 v113, v113
	v_rcp_f32_e32 v106, v106
	v_rcp_f32_e32 v107, v107
	v_rcp_f32_e32 v108, v108
	v_rcp_f32_e32 v109, v109
	v_max_f32_e32 v110, 0x219392ef, v110
	v_max_f32_e32 v111, 0x219392ef, v111
	v_max_f32_e32 v112, 0x219392ef, v112
	v_max_f32_e32 v113, 0x219392ef, v113
	v_max_f32_e32 v106, 0x219392ef, v106
	v_max_f32_e32 v107, 0x219392ef, v107
	v_max_f32_e32 v108, 0x219392ef, v108
	v_max_f32_e32 v109, 0x219392ef, v109
	v_cvt_pk_bf16_f32 v110, v110, v111
	v_cvt_pk_bf16_f32 v111, v112, v113
	v_cvt_pk_bf16_f32 v112, v106, v107
	v_cvt_pk_bf16_f32 v113, v108, v109
	global_store_dwordx4 v[158:159], v[110:113], off sc1
	v_pk_fma_f32 v[86:87], v[86:87], s[60:61], v[94:95]
	v_pk_fma_f32 v[88:89], v[88:89], s[60:61], v[96:97]
	v_pk_fma_f32 v[82:83], v[82:83], s[60:61], v[90:91]
	v_pk_fma_f32 v[84:85], v[84:85], s[60:61], v[92:93]
	v_exp_f32_e32 v86, v86
	v_exp_f32_e32 v87, v87
	v_exp_f32_e32 v88, v88
	v_exp_f32_e32 v89, v89
	v_exp_f32_e32 v82, v82
	v_exp_f32_e32 v83, v83
	v_exp_f32_e32 v84, v84
	v_exp_f32_e32 v85, v85
	v_pk_add_f32 v[86:87], v[86:87], 1.0 op_sel_hi:[1,0]
	v_pk_add_f32 v[88:89], v[88:89], 1.0 op_sel_hi:[1,0]
	v_pk_add_f32 v[82:83], v[82:83], 1.0 op_sel_hi:[1,0]
	v_pk_add_f32 v[84:85], v[84:85], 1.0 op_sel_hi:[1,0]
	v_rcp_f32_e32 v86, v86
	v_rcp_f32_e32 v87, v87
	v_rcp_f32_e32 v88, v88
	v_rcp_f32_e32 v89, v89
	v_rcp_f32_e32 v82, v82
	v_rcp_f32_e32 v83, v83
	v_rcp_f32_e32 v84, v84
	v_rcp_f32_e32 v85, v85
	v_max_f32_e32 v86, 0x219392ef, v86
	v_max_f32_e32 v87, 0x219392ef, v87
	v_max_f32_e32 v88, 0x219392ef, v88
	v_max_f32_e32 v89, 0x219392ef, v89
	v_max_f32_e32 v82, 0x219392ef, v82
	v_max_f32_e32 v83, 0x219392ef, v83
	v_max_f32_e32 v84, 0x219392ef, v84
	v_max_f32_e32 v85, 0x219392ef, v85
	v_cvt_pk_bf16_f32 v86, v86, v87
	v_cvt_pk_bf16_f32 v87, v88, v89
	v_cvt_pk_bf16_f32 v88, v82, v83
	v_cvt_pk_bf16_f32 v89, v84, v85
	global_store_dwordx4 v[158:159], v[86:89], off offset:1024 sc1
	v_pk_fma_f32 v[78:79], v[78:79], s[60:61], v[102:103]
	v_pk_fma_f32 v[80:81], v[80:81], s[60:61], v[104:105]
	v_pk_fma_f32 v[74:75], v[74:75], s[60:61], v[98:99]
	v_pk_fma_f32 v[76:77], v[76:77], s[60:61], v[100:101]
	v_exp_f32_e32 v78, v78
	v_exp_f32_e32 v79, v79
	v_exp_f32_e32 v80, v80
	v_exp_f32_e32 v81, v81
	v_exp_f32_e32 v74, v74
	v_exp_f32_e32 v75, v75
	v_exp_f32_e32 v76, v76
	v_exp_f32_e32 v77, v77
	v_pk_add_f32 v[78:79], v[78:79], 1.0 op_sel_hi:[1,0]
	v_pk_add_f32 v[80:81], v[80:81], 1.0 op_sel_hi:[1,0]
	v_pk_add_f32 v[74:75], v[74:75], 1.0 op_sel_hi:[1,0]
	v_pk_add_f32 v[76:77], v[76:77], 1.0 op_sel_hi:[1,0]
	v_rcp_f32_e32 v78, v78
	v_rcp_f32_e32 v79, v79
	v_rcp_f32_e32 v80, v80
	v_rcp_f32_e32 v81, v81
	v_rcp_f32_e32 v74, v74
	v_rcp_f32_e32 v75, v75
	v_rcp_f32_e32 v76, v76
	v_rcp_f32_e32 v77, v77
	v_max_f32_e32 v78, 0x219392ef, v78
	v_max_f32_e32 v79, 0x219392ef, v79
	v_max_f32_e32 v80, 0x219392ef, v80
	v_max_f32_e32 v81, 0x219392ef, v81
	v_max_f32_e32 v74, 0x219392ef, v74
	v_max_f32_e32 v75, 0x219392ef, v75
	v_max_f32_e32 v76, 0x219392ef, v76
	v_max_f32_e32 v77, 0x219392ef, v77
	v_cvt_pk_bf16_f32 v78, v78, v79
	v_cvt_pk_bf16_f32 v79, v80, v81
	v_cvt_pk_bf16_f32 v80, v74, v75
	v_cvt_pk_bf16_f32 v81, v76, v77
	global_store_dwordx4 v[158:159], v[78:81], off offset:2048 sc1
	v_pk_fma_f32 v[70:71], v[70:71], s[60:61], v[94:95]
	v_pk_fma_f32 v[72:73], v[72:73], s[60:61], v[96:97]
	v_pk_fma_f32 v[66:67], v[66:67], s[60:61], v[90:91]
	v_pk_fma_f32 v[68:69], v[68:69], s[60:61], v[92:93]
	v_exp_f32_e32 v70, v70
	v_exp_f32_e32 v71, v71
	v_exp_f32_e32 v72, v72
	v_exp_f32_e32 v73, v73
	v_exp_f32_e32 v66, v66
	v_exp_f32_e32 v67, v67
	v_exp_f32_e32 v68, v68
	v_exp_f32_e32 v69, v69
	v_pk_add_f32 v[70:71], v[70:71], 1.0 op_sel_hi:[1,0]
	v_pk_add_f32 v[72:73], v[72:73], 1.0 op_sel_hi:[1,0]
	v_pk_add_f32 v[66:67], v[66:67], 1.0 op_sel_hi:[1,0]
	v_pk_add_f32 v[68:69], v[68:69], 1.0 op_sel_hi:[1,0]
	v_rcp_f32_e32 v70, v70
	v_rcp_f32_e32 v71, v71
	v_rcp_f32_e32 v72, v72
	v_rcp_f32_e32 v73, v73
	v_rcp_f32_e32 v66, v66
	v_rcp_f32_e32 v67, v67
	v_rcp_f32_e32 v68, v68
	v_rcp_f32_e32 v69, v69
	v_max_f32_e32 v70, 0x219392ef, v70
	v_max_f32_e32 v71, 0x219392ef, v71
	v_max_f32_e32 v72, 0x219392ef, v72
	v_max_f32_e32 v73, 0x219392ef, v73
	v_max_f32_e32 v66, 0x219392ef, v66
	v_max_f32_e32 v67, 0x219392ef, v67
	v_max_f32_e32 v68, 0x219392ef, v68
	v_max_f32_e32 v69, 0x219392ef, v69
	v_cvt_pk_bf16_f32 v70, v70, v71
	v_cvt_pk_bf16_f32 v71, v72, v73
	v_cvt_pk_bf16_f32 v72, v66, v67
	v_cvt_pk_bf16_f32 v73, v68, v69
	global_store_dwordx4 v[158:159], v[70:73], off offset:3072 sc1
	v_add_co_u32_e32 v158, vcc, 0x2000, v158
	s_nop 1
	v_addc_co_u32_e32 v159, vcc, 0, v159, vcc
	v_pk_fma_f32 v[62:63], v[62:63], s[60:61], v[102:103]
	v_pk_fma_f32 v[64:65], v[64:65], s[60:61], v[104:105]
	v_pk_fma_f32 v[58:59], v[58:59], s[60:61], v[98:99]
	v_pk_fma_f32 v[60:61], v[60:61], s[60:61], v[100:101]
	v_exp_f32_e32 v62, v62
	v_exp_f32_e32 v63, v63
	v_exp_f32_e32 v64, v64
	v_exp_f32_e32 v65, v65
	v_exp_f32_e32 v58, v58
	v_exp_f32_e32 v59, v59
	v_exp_f32_e32 v60, v60
	v_exp_f32_e32 v61, v61
	v_pk_add_f32 v[62:63], v[62:63], 1.0 op_sel_hi:[1,0]
	v_pk_add_f32 v[64:65], v[64:65], 1.0 op_sel_hi:[1,0]
	v_pk_add_f32 v[58:59], v[58:59], 1.0 op_sel_hi:[1,0]
	v_pk_add_f32 v[60:61], v[60:61], 1.0 op_sel_hi:[1,0]
	v_rcp_f32_e32 v62, v62
	v_rcp_f32_e32 v63, v63
	v_rcp_f32_e32 v64, v64
	v_rcp_f32_e32 v65, v65
	v_rcp_f32_e32 v58, v58
	v_rcp_f32_e32 v59, v59
	v_rcp_f32_e32 v60, v60
	v_rcp_f32_e32 v61, v61
	v_max_f32_e32 v62, 0x219392ef, v62
	v_max_f32_e32 v63, 0x219392ef, v63
	v_max_f32_e32 v64, 0x219392ef, v64
	v_max_f32_e32 v65, 0x219392ef, v65
	v_max_f32_e32 v58, 0x219392ef, v58
	v_max_f32_e32 v59, 0x219392ef, v59
	v_max_f32_e32 v60, 0x219392ef, v60
	v_max_f32_e32 v61, 0x219392ef, v61
	v_cvt_pk_bf16_f32 v62, v62, v63
	v_cvt_pk_bf16_f32 v63, v64, v65
	v_cvt_pk_bf16_f32 v64, v58, v59
	v_cvt_pk_bf16_f32 v65, v60, v61
	global_store_dwordx4 v[158:159], v[62:65], off offset:-4096 sc1
	v_pk_fma_f32 v[54:55], v[54:55], s[60:61], v[94:95]
	v_pk_fma_f32 v[56:57], v[56:57], s[60:61], v[96:97]
	v_pk_fma_f32 v[50:51], v[50:51], s[60:61], v[90:91]
	v_pk_fma_f32 v[52:53], v[52:53], s[60:61], v[92:93]
	v_exp_f32_e32 v54, v54
	v_exp_f32_e32 v55, v55
	v_exp_f32_e32 v56, v56
	v_exp_f32_e32 v57, v57
	v_exp_f32_e32 v50, v50
	v_exp_f32_e32 v51, v51
	v_exp_f32_e32 v52, v52
	v_exp_f32_e32 v53, v53
	v_pk_add_f32 v[54:55], v[54:55], 1.0 op_sel_hi:[1,0]
	v_pk_add_f32 v[56:57], v[56:57], 1.0 op_sel_hi:[1,0]
	v_pk_add_f32 v[50:51], v[50:51], 1.0 op_sel_hi:[1,0]
	v_pk_add_f32 v[52:53], v[52:53], 1.0 op_sel_hi:[1,0]
	v_rcp_f32_e32 v54, v54
	v_rcp_f32_e32 v55, v55
	v_rcp_f32_e32 v56, v56
	v_rcp_f32_e32 v57, v57
	v_rcp_f32_e32 v50, v50
	v_rcp_f32_e32 v51, v51
	v_rcp_f32_e32 v52, v52
	v_rcp_f32_e32 v53, v53
	v_max_f32_e32 v54, 0x219392ef, v54
	v_max_f32_e32 v55, 0x219392ef, v55
	v_max_f32_e32 v56, 0x219392ef, v56
	v_max_f32_e32 v57, 0x219392ef, v57
	v_max_f32_e32 v50, 0x219392ef, v50
	v_max_f32_e32 v51, 0x219392ef, v51
	v_max_f32_e32 v52, 0x219392ef, v52
	v_max_f32_e32 v53, 0x219392ef, v53
	v_cvt_pk_bf16_f32 v54, v54, v55
	v_cvt_pk_bf16_f32 v55, v56, v57
	v_cvt_pk_bf16_f32 v56, v50, v51
	v_cvt_pk_bf16_f32 v57, v52, v53
	global_store_dwordx4 v[158:159], v[54:57], off offset:-3072 sc1
	v_pk_fma_f32 v[46:47], v[46:47], s[60:61], v[102:103]
	v_pk_fma_f32 v[48:49], v[48:49], s[60:61], v[104:105]
	v_pk_fma_f32 v[42:43], v[42:43], s[60:61], v[98:99]
	v_pk_fma_f32 v[44:45], v[44:45], s[60:61], v[100:101]
	v_exp_f32_e32 v46, v46
	v_exp_f32_e32 v47, v47
	v_exp_f32_e32 v48, v48
	v_exp_f32_e32 v49, v49
	v_exp_f32_e32 v42, v42
	v_exp_f32_e32 v43, v43
	v_exp_f32_e32 v44, v44
	v_exp_f32_e32 v45, v45
	v_pk_add_f32 v[46:47], v[46:47], 1.0 op_sel_hi:[1,0]
	v_pk_add_f32 v[48:49], v[48:49], 1.0 op_sel_hi:[1,0]
	v_pk_add_f32 v[42:43], v[42:43], 1.0 op_sel_hi:[1,0]
	v_pk_add_f32 v[44:45], v[44:45], 1.0 op_sel_hi:[1,0]
	v_rcp_f32_e32 v46, v46
	v_rcp_f32_e32 v47, v47
	v_rcp_f32_e32 v48, v48
	v_rcp_f32_e32 v49, v49
	v_rcp_f32_e32 v42, v42
	v_rcp_f32_e32 v43, v43
	v_rcp_f32_e32 v44, v44
	v_rcp_f32_e32 v45, v45
	v_max_f32_e32 v46, 0x219392ef, v46
	v_max_f32_e32 v47, 0x219392ef, v47
	v_max_f32_e32 v48, 0x219392ef, v48
	v_max_f32_e32 v49, 0x219392ef, v49
	v_max_f32_e32 v42, 0x219392ef, v42
	v_max_f32_e32 v43, 0x219392ef, v43
	v_max_f32_e32 v44, 0x219392ef, v44
	v_max_f32_e32 v45, 0x219392ef, v45
	v_cvt_pk_bf16_f32 v46, v46, v47
	v_cvt_pk_bf16_f32 v47, v48, v49
	v_cvt_pk_bf16_f32 v48, v42, v43
	v_cvt_pk_bf16_f32 v49, v44, v45
	global_store_dwordx4 v[158:159], v[46:49], off offset:-2048 sc1
	v_pk_fma_f32 v[38:39], v[38:39], s[60:61], v[94:95]
	v_pk_fma_f32 v[40:41], v[40:41], s[60:61], v[96:97]
	v_pk_fma_f32 v[34:35], v[34:35], s[60:61], v[90:91]
	v_pk_fma_f32 v[36:37], v[36:37], s[60:61], v[92:93]
	v_exp_f32_e32 v38, v38
	v_exp_f32_e32 v39, v39
	v_exp_f32_e32 v40, v40
	v_exp_f32_e32 v41, v41
	v_exp_f32_e32 v34, v34
	v_exp_f32_e32 v35, v35
	v_exp_f32_e32 v36, v36
	v_exp_f32_e32 v37, v37
	v_pk_add_f32 v[38:39], v[38:39], 1.0 op_sel_hi:[1,0]
	v_pk_add_f32 v[40:41], v[40:41], 1.0 op_sel_hi:[1,0]
	v_pk_add_f32 v[34:35], v[34:35], 1.0 op_sel_hi:[1,0]
	v_pk_add_f32 v[36:37], v[36:37], 1.0 op_sel_hi:[1,0]
	v_rcp_f32_e32 v38, v38
	v_rcp_f32_e32 v39, v39
	v_rcp_f32_e32 v40, v40
	v_rcp_f32_e32 v41, v41
	v_rcp_f32_e32 v34, v34
	v_rcp_f32_e32 v35, v35
	v_rcp_f32_e32 v36, v36
	v_rcp_f32_e32 v37, v37
	v_max_f32_e32 v38, 0x219392ef, v38
	v_max_f32_e32 v39, 0x219392ef, v39
	v_max_f32_e32 v40, 0x219392ef, v40
	v_max_f32_e32 v41, 0x219392ef, v41
	v_max_f32_e32 v34, 0x219392ef, v34
	v_max_f32_e32 v35, 0x219392ef, v35
	v_max_f32_e32 v36, 0x219392ef, v36
	v_max_f32_e32 v37, 0x219392ef, v37
	v_cvt_pk_bf16_f32 v38, v38, v39
	v_cvt_pk_bf16_f32 v39, v40, v41
	v_cvt_pk_bf16_f32 v40, v34, v35
	v_cvt_pk_bf16_f32 v41, v36, v37
	global_store_dwordx4 v[158:159], v[38:41], off offset:-1024 sc1
	v_pk_fma_f32 v[30:31], v[30:31], s[60:61], v[102:103]
	v_pk_fma_f32 v[32:33], v[32:33], s[60:61], v[104:105]
	v_pk_fma_f32 v[26:27], v[26:27], s[60:61], v[98:99]
	v_pk_fma_f32 v[28:29], v[28:29], s[60:61], v[100:101]
	v_exp_f32_e32 v30, v30
	v_exp_f32_e32 v31, v31
	v_exp_f32_e32 v32, v32
	v_exp_f32_e32 v33, v33
	v_exp_f32_e32 v26, v26
	v_exp_f32_e32 v27, v27
	v_exp_f32_e32 v28, v28
	v_exp_f32_e32 v29, v29
	v_pk_add_f32 v[30:31], v[30:31], 1.0 op_sel_hi:[1,0]
	v_pk_add_f32 v[32:33], v[32:33], 1.0 op_sel_hi:[1,0]
	v_pk_add_f32 v[26:27], v[26:27], 1.0 op_sel_hi:[1,0]
	v_pk_add_f32 v[28:29], v[28:29], 1.0 op_sel_hi:[1,0]
	v_rcp_f32_e32 v30, v30
	v_rcp_f32_e32 v31, v31
	v_rcp_f32_e32 v32, v32
	v_rcp_f32_e32 v33, v33
	v_rcp_f32_e32 v26, v26
	v_rcp_f32_e32 v27, v27
	v_rcp_f32_e32 v28, v28
	v_rcp_f32_e32 v29, v29
	v_max_f32_e32 v30, 0x219392ef, v30
	v_max_f32_e32 v31, 0x219392ef, v31
	v_max_f32_e32 v32, 0x219392ef, v32
	v_max_f32_e32 v33, 0x219392ef, v33
	v_max_f32_e32 v26, 0x219392ef, v26
	v_max_f32_e32 v27, 0x219392ef, v27
	v_max_f32_e32 v28, 0x219392ef, v28
	v_max_f32_e32 v29, 0x219392ef, v29
	v_cvt_pk_bf16_f32 v30, v30, v31
	v_cvt_pk_bf16_f32 v31, v32, v33
	v_cvt_pk_bf16_f32 v32, v26, v27
	v_cvt_pk_bf16_f32 v33, v28, v29
	global_store_dwordx4 v[158:159], v[30:33], off sc1
	v_pk_fma_f32 v[22:23], v[22:23], s[60:61], v[94:95]
	v_pk_fma_f32 v[24:25], v[24:25], s[60:61], v[96:97]
	v_pk_fma_f32 v[18:19], v[18:19], s[60:61], v[90:91]
	v_pk_fma_f32 v[20:21], v[20:21], s[60:61], v[92:93]
	v_exp_f32_e32 v22, v22
	v_exp_f32_e32 v23, v23
	v_exp_f32_e32 v24, v24
	v_exp_f32_e32 v25, v25
	v_exp_f32_e32 v18, v18
	v_exp_f32_e32 v19, v19
	v_exp_f32_e32 v20, v20
	v_exp_f32_e32 v21, v21
	v_pk_add_f32 v[22:23], v[22:23], 1.0 op_sel_hi:[1,0]
	v_pk_add_f32 v[24:25], v[24:25], 1.0 op_sel_hi:[1,0]
	v_pk_add_f32 v[18:19], v[18:19], 1.0 op_sel_hi:[1,0]
	v_pk_add_f32 v[20:21], v[20:21], 1.0 op_sel_hi:[1,0]
	v_rcp_f32_e32 v22, v22
	v_rcp_f32_e32 v23, v23
	v_rcp_f32_e32 v24, v24
	v_rcp_f32_e32 v25, v25
	v_rcp_f32_e32 v18, v18
	v_rcp_f32_e32 v19, v19
	v_rcp_f32_e32 v20, v20
	v_rcp_f32_e32 v21, v21
	v_max_f32_e32 v22, 0x219392ef, v22
	v_max_f32_e32 v23, 0x219392ef, v23
	v_max_f32_e32 v24, 0x219392ef, v24
	v_max_f32_e32 v25, 0x219392ef, v25
	v_max_f32_e32 v18, 0x219392ef, v18
	v_max_f32_e32 v19, 0x219392ef, v19
	v_max_f32_e32 v20, 0x219392ef, v20
	v_max_f32_e32 v21, 0x219392ef, v21
	v_cvt_pk_bf16_f32 v22, v22, v23
	v_cvt_pk_bf16_f32 v23, v24, v25
	v_cvt_pk_bf16_f32 v24, v18, v19
	v_cvt_pk_bf16_f32 v25, v20, v21
	global_store_dwordx4 v[158:159], v[22:25], off offset:1024 sc1
	v_pk_fma_f32 v[14:15], v[14:15], s[60:61], v[102:103]
	v_pk_fma_f32 v[16:17], v[16:17], s[60:61], v[104:105]
	v_pk_fma_f32 v[10:11], v[10:11], s[60:61], v[98:99]
	v_pk_fma_f32 v[12:13], v[12:13], s[60:61], v[100:101]
	v_exp_f32_e32 v14, v14
	v_exp_f32_e32 v15, v15
	v_exp_f32_e32 v16, v16
	v_exp_f32_e32 v17, v17
	v_exp_f32_e32 v10, v10
	v_exp_f32_e32 v11, v11
	v_exp_f32_e32 v12, v12
	v_exp_f32_e32 v13, v13
	v_pk_add_f32 v[14:15], v[14:15], 1.0 op_sel_hi:[1,0]
	v_pk_add_f32 v[16:17], v[16:17], 1.0 op_sel_hi:[1,0]
	v_pk_add_f32 v[10:11], v[10:11], 1.0 op_sel_hi:[1,0]
	v_pk_add_f32 v[12:13], v[12:13], 1.0 op_sel_hi:[1,0]
	v_rcp_f32_e32 v14, v14
	v_rcp_f32_e32 v15, v15
	v_rcp_f32_e32 v16, v16
	v_rcp_f32_e32 v17, v17
	v_rcp_f32_e32 v10, v10
	v_rcp_f32_e32 v11, v11
	v_rcp_f32_e32 v12, v12
	v_rcp_f32_e32 v13, v13
	v_max_f32_e32 v14, 0x219392ef, v14
	v_max_f32_e32 v15, 0x219392ef, v15
	v_max_f32_e32 v16, 0x219392ef, v16
	v_max_f32_e32 v17, 0x219392ef, v17
	v_max_f32_e32 v10, 0x219392ef, v10
	v_max_f32_e32 v11, 0x219392ef, v11
	v_max_f32_e32 v12, 0x219392ef, v12
	v_max_f32_e32 v13, 0x219392ef, v13
	v_cvt_pk_bf16_f32 v14, v14, v15
	v_cvt_pk_bf16_f32 v15, v16, v17
	v_cvt_pk_bf16_f32 v16, v10, v11
	v_cvt_pk_bf16_f32 v17, v12, v13
	global_store_dwordx4 v[158:159], v[14:17], off offset:2048 sc1
	v_pk_fma_f32 v[6:7], v[6:7], s[60:61], v[94:95]
	v_pk_fma_f32 v[8:9], v[8:9], s[60:61], v[96:97]
	v_pk_fma_f32 v[2:3], v[2:3], s[60:61], v[90:91]
	v_pk_fma_f32 v[4:5], v[4:5], s[60:61], v[92:93]
	v_exp_f32_e32 v6, v6
	v_exp_f32_e32 v7, v7
	v_exp_f32_e32 v8, v8
	v_exp_f32_e32 v9, v9
	v_exp_f32_e32 v2, v2
	v_exp_f32_e32 v3, v3
	v_exp_f32_e32 v4, v4
	v_exp_f32_e32 v5, v5
	v_pk_add_f32 v[6:7], v[6:7], 1.0 op_sel_hi:[1,0]
	v_pk_add_f32 v[8:9], v[8:9], 1.0 op_sel_hi:[1,0]
	v_pk_add_f32 v[2:3], v[2:3], 1.0 op_sel_hi:[1,0]
	v_pk_add_f32 v[4:5], v[4:5], 1.0 op_sel_hi:[1,0]
	v_rcp_f32_e32 v6, v6
	v_rcp_f32_e32 v7, v7
	v_rcp_f32_e32 v8, v8
	v_rcp_f32_e32 v9, v9
	v_rcp_f32_e32 v2, v2
	v_rcp_f32_e32 v3, v3
	v_rcp_f32_e32 v4, v4
	v_rcp_f32_e32 v5, v5
	v_max_f32_e32 v6, 0x219392ef, v6
	v_max_f32_e32 v7, 0x219392ef, v7
	v_max_f32_e32 v8, 0x219392ef, v8
	v_max_f32_e32 v9, 0x219392ef, v9
	v_max_f32_e32 v2, 0x219392ef, v2
	v_max_f32_e32 v3, 0x219392ef, v3
	v_max_f32_e32 v4, 0x219392ef, v4
	v_max_f32_e32 v5, 0x219392ef, v5
	v_cvt_pk_bf16_f32 v6, v6, v7
	v_cvt_pk_bf16_f32 v7, v8, v9
	v_cvt_pk_bf16_f32 v8, v2, v3
	v_cvt_pk_bf16_f32 v9, v4, v5
	global_store_dwordx4 v[158:159], v[6:9], off offset:3072 sc1
	s_andn2_b64 vcc, exec, s[38:39]
	s_mov_b64 s[38:39], -1
	s_cbranch_vccnz .LBB0_533
	s_andn2_b64 vcc, exec, s[26:27]
	s_cbranch_vccnz .LBB0_532
	s_barrier
	s_branch .LBB0_532
